# retention LDS-read pipelining (jt V reads hoisted, cross-term double-buffered) + step-0 streaming loops (p->bf16 unrolled x4, x->bf16 row loads issued together); SWA edits dropped
# speedup vs baseline: 1.0089x; 1.0048x over previous
.LBB0_266:
	s_mul_i32 s3, s56, 3
	s_add_i32 s3, s3, s2
	s_cmpk_gt_i32 s3, 0x7fff
	s_cbranch_scc1 .Lpb_tail
	global_load_dwordx4 v[4:7], v[2:3], off
	v_lshl_add_u64 v[148:149], v[2:3], 0, s[10:11]
	global_load_dwordx4 v[152:155], v[148:149], off
	v_lshl_add_u64 v[148:149], v[148:149], 0, s[10:11]
	global_load_dwordx4 v[156:159], v[148:149], off
	v_lshl_add_u64 v[148:149], v[148:149], 0, s[10:11]
	global_load_dwordx4 v[160:163], v[148:149], off
	v_lshl_add_u64 v[2:3], v[148:149], 0, s[10:11]
	s_lshl_b32 s3, s56, 2
	s_add_i32 s2, s2, s3
	s_waitcnt vmcnt(0)
	v_cvt_pk_bf16_f32 v4, v4, v5
	v_cvt_pk_bf16_f32 v5, v6, v7
	global_store_dwordx2 v[0:1], v[4:5], off
	v_lshl_add_u64 v[0:1], v[0:1], 0, s[8:9]
	v_cvt_pk_bf16_f32 v152, v152, v153
	v_cvt_pk_bf16_f32 v153, v154, v155
	global_store_dwordx2 v[0:1], v[152:153], off
	v_lshl_add_u64 v[0:1], v[0:1], 0, s[8:9]
	v_cvt_pk_bf16_f32 v156, v156, v157
	v_cvt_pk_bf16_f32 v157, v158, v159
	global_store_dwordx2 v[0:1], v[156:157], off
	v_lshl_add_u64 v[0:1], v[0:1], 0, s[8:9]
	v_cvt_pk_bf16_f32 v160, v160, v161
	v_cvt_pk_bf16_f32 v161, v162, v163
	global_store_dwordx2 v[0:1], v[160:161], off
	v_lshl_add_u64 v[0:1], v[0:1], 0, s[8:9]
	s_branch .LBB0_266
.Lpb_tail:
	s_cmpk_gt_i32 s2, 0x7fff
	s_cbranch_scc1 .LBB0_267

.LBB0_271:
	s_waitcnt lgkmcnt(0)
	global_load_dwordx4 v[4:7], v[2:3], off offset:-2048
	global_load_dwordx4 v[152:155], v[2:3], off offset:-1024
	global_load_dwordx4 v[156:159], v[2:3], off
	global_load_dwordx4 v[160:163], v[2:3], off offset:1024
	v_lshl_add_u64 v[8:9], s[94:95], 0, v[0:1]
	s_mov_b32 s4, 0x3800000
	v_add_co_u32_e32 v20, vcc, s4, v8
	s_waitcnt vmcnt(3)
	v_cvt_pk_bf16_f32 v8, v4, v5
	v_addc_co_u32_e32 v21, vcc, 0, v9, vcc
	v_cvt_pk_bf16_f32 v9, v6, v7
	global_store_dwordx2 v[20:21], v[8:9], off
	v_mul_f32_e32 v5, v5, v5
	v_mul_f32_e32 v7, v7, v7
	v_fmac_f32_e32 v5, v4, v4
	v_fmac_f32_e32 v7, v6, v6
	v_add_f32_e32 v4, v5, v7
	s_waitcnt vmcnt(3)
	v_cvt_pk_bf16_f32 v12, v152, v153
	v_cvt_pk_bf16_f32 v13, v154, v155
	global_store_dwordx2 v[20:21], v[12:13], off offset:512
	v_mul_f32_e32 v5, v153, v153
	v_mul_f32_e32 v6, v155, v155
	v_fmac_f32_e32 v5, v152, v152
	v_fmac_f32_e32 v6, v154, v154
	v_add_f32_e32 v5, v5, v6
	v_add_f32_e32 v4, v4, v5
	s_waitcnt vmcnt(3)
	v_cvt_pk_bf16_f32 v16, v156, v157
	v_cvt_pk_bf16_f32 v17, v158, v159
	global_store_dwordx2 v[20:21], v[16:17], off offset:1024
	v_mul_f32_e32 v5, v157, v157
	v_mul_f32_e32 v6, v159, v159
	v_fmac_f32_e32 v5, v156, v156
	v_fmac_f32_e32 v6, v158, v158
	v_add_f32_e32 v5, v5, v6
	v_add_f32_e32 v4, v4, v5
	s_waitcnt vmcnt(3)
	v_mul_f32_e32 v5, v161, v161
	v_mul_f32_e32 v6, v163, v163
	v_fmac_f32_e32 v5, v160, v160
	v_fmac_f32_e32 v6, v162, v162
	v_add_f32_e32 v5, v5, v6
	v_add_f32_e32 v4, v4, v5
	ds_bpermute_b32 v5, v222, v4
	v_cvt_pk_bf16_f32 v6, v160, v161
	v_cvt_pk_bf16_f32 v7, v162, v163
	global_store_dwordx2 v[20:21], v[6:7], off offset:1536
	s_waitcnt lgkmcnt(0)
	v_add_f32_e32 v4, v4, v5
	ds_bpermute_b32 v5, v223, v4
	s_waitcnt lgkmcnt(0)
	v_add_f32_e32 v4, v4, v5
	ds_bpermute_b32 v5, v224, v4
	s_waitcnt lgkmcnt(0)
	v_add_f32_e32 v4, v4, v5
	ds_bpermute_b32 v5, v225, v4
	s_waitcnt lgkmcnt(0)
	v_add_f32_e32 v4, v4, v5
	ds_bpermute_b32 v5, v226, v4
	s_waitcnt lgkmcnt(0)
	v_add_f32_e32 v4, v4, v5
	ds_bpermute_b32 v5, v227, v4
	s_and_saveexec_b64 s[4:5], s[0:1]
	s_cbranch_execz .LBB0_270
	s_add_u32 s8, s94, s2
	s_addc_u32 s9, s95, s3
	s_waitcnt lgkmcnt(0)
	v_add_f32_e32 v4, v4, v5
	global_store_dword v145, v4, s[8:9]
	s_branch .LBB0_270
